# retention-output units: the per-unit scan-counter poll + acquire replaced by one poll of all twelve counters (plus the tail-tile counter) and one acquire at the start of the part
# speedup vs baseline: 1.0040x; 1.0040x over previous
; __device__ __forceinline__ const float* karg(int k) { int kk = k; asm volatile("" : "+s"(kk)); return ((const float* const __attribute__((address_space(4)))*)__builtin_amdgcn_kernarg_segment_ptr())[kk]; }
; __device__ __forceinline__ void wait_ge(unsigned* word, unsigned want, unsigned* tmo) {
;     if (threadIdx.x == 0) {
;         unsigned sp = 0;
;         while (__hip_atomic_load(word, __ATOMIC_RELAXED, __HIP_MEMORY_SCOPE_AGENT) < want) {
;             __builtin_amdgcn_s_sleep(2);
;             if (++sp > (1u << 21)) { __hip_atomic_store(tmo, 1u, __ATOMIC_RELAXED, __HIP_MEMORY_SCOPE_AGENT); break; }
;             if ((sp & 1023u) == 0u && __hip_atomic_load(tmo, __ATOMIC_RELAXED, __HIP_MEMORY_SCOPE_AGENT)) break;
;         }
;         __builtin_amdgcn_fence(__ATOMIC_ACQUIRE, "agent");
;         asm volatile("s_waitcnt vmcnt(0)" ::: "memory");
; __global__ void __launch_bounds__(NTHR, 2) fwd(Args args) {
;     ...
;                 if (u < 768) { wait_ge(cw + 128 + (u >> 6), 8u, cw + 192); ret_unit(lds, PROJ, RT, karg(3) + l * 768, CAT, u); }
.Lxtail_wait_loop:
	global_load_dword v0, v1, s[4:5] offset:3584 sc1
	global_load_dwordx4 v[2:5], v1, s[4:5] offset:768 sc1
	global_load_dwordx4 v[6:9], v1, s[4:5] offset:784 sc1
	global_load_dwordx4 v[10:13], v1, s[4:5] offset:800 sc1
	s_waitcnt vmcnt(0)
	v_min_u32_e32 v2, v2, v3
	v_min_u32_e32 v4, v4, v5
	v_min_u32_e32 v6, v6, v7
	v_min_u32_e32 v8, v8, v9
	v_min_u32_e32 v10, v10, v11
	v_min_u32_e32 v12, v12, v13
	v_min_u32_e32 v2, v2, v4
	v_min_u32_e32 v6, v6, v8
	v_min_u32_e32 v10, v10, v12
	v_min3_u32 v2, v2, v6, v10
	v_readfirstlane_b32 s22, v0
	s_nop 0
	v_readfirstlane_b32 s20, v2
	s_cmp_ge_u32 s22, 64
	s_cselect_b32 s22, 1, 0
	s_cmp_ge_u32 s20, 8
	s_cselect_b32 s20, 1, 0
	s_and_b32 s22, s22, s20
	s_cmp_lg_u32 s22, 0
	s_cbranch_scc1 .Lxtail_wait_ok
	s_sleep 2
	s_add_u32 s23, s23, 1
	s_cmp_lt_u32 s23, 0x4000
	s_cbranch_scc1 .Lxtail_wait_loop

; #define LAS __attribute__((address_space(3)))
; __device__ __forceinline__ float ret_log2gamma(int h) { return log2f(1.f - exp2f(-5.f - (float)h)); }
; __device__ __forceinline__ const float* karg(int k) { int kk = k; asm volatile("" : "+s"(kk)); return ((const float* const __attribute__((address_space(4)))*)__builtin_amdgcn_kernarg_segment_ptr())[kk]; }
; __device__ __forceinline__ void ret_unit(LAS unsigned char* lds, const bfu* PROJ, const bfu* RT, const float* gn_g, bfu* CAT, int u) {
;     ...
;     const int bh = u >> 6, i = u & 63, b = bh / 6, h = bh % 6; const size_t row0 = (size_t)b * SEQ + (size_t)i * 128; const float lg = ret_log2gamma(h);
;     LAS bfu* Qs = (LAS bfu*)lds; LAS bfu* Ks = (LAS bfu*)(lds + TILE_B); LAS bfu* Vt = (LAS bfu*)(lds + 2 * TILE_B); LAS bfu* Rt = (LAS bfu*)(lds + 3 * TILE_B);
;     const bfu* P0 = PROJ + row0 * INW + h * 128;
;     stage_nat(Qs, P0 + C_RQ, INW, tid); stage_nat(Ks, P0 + C_RK, INW, tid); stage_tr<false>(Vt, P0 + C_RV, INW, tid, 0.f); stage_nat(Rt, RT + (size_t)u * 16384, 128, tid);
; __global__ void __launch_bounds__(NTHR, 2) fwd(Args args) {
;     ...
;                 if (u < 768) { wait_ge(cw + 128 + (u >> 6), 8u, cw + 192); ret_unit(lds, PROJ, RT, karg(3) + l * 768, CAT, u); }
.Lxtail_wait_done:
	s_or_b64 exec, exec, s[34:35]
	s_barrier
	v_readlane_b32 s22, v255, 30
	s_lshl_b32 s26, s22, 16
	s_lshl_b32 s20, s22, 9
	s_mulk_i32 s22, 0x300
	s_mov_b32 s23, s21
	s_lshl_b32 s55, s26, 1
	s_lshl_b64 s[26:27], s[20:21], 2
	s_lshl_b64 s[36:37], s[22:23], 2
	s_branch .LBB0_413
.LBB0_410:
	s_or_b64 exec, exec, s[40:41]
	s_mov_b32 s22, 21
	s_barrier
	s_ashr_i32 s23, s22, 31
	s_lshl_b64 s[22:23], s[22:23], 3
	s_add_u32 s22, s0, s22
	s_addc_u32 s23, s1, s23
	s_load_dwordx2 s[48:49], s[22:23], 0x0
	s_mov_b32 s22, 21
	s_ashr_i32 s23, s22, 31
	s_lshl_b64 s[22:23], s[22:23], 3
	s_add_u32 s22, s0, s22
	s_addc_u32 s23, s1, s23
	s_load_dwordx2 s[40:41], s[22:23], 0x0
	s_mov_b32 s22, 3
	s_ashr_i32 s23, s22, 31
	s_lshl_b64 s[22:23], s[22:23], 3
	s_add_u32 s22, s0, s22
	s_addc_u32 s23, s1, s23
	s_load_dwordx2 s[22:23], s[22:23], 0x0
	v_mov_b32_e32 v10, v232
	v_readlane_b32 s91, v255, 54
	s_waitcnt lgkmcnt(0)
	s_add_u32 s20, s22, s36
	s_mov_b32 s22, 21
	s_addc_u32 s35, s23, s37
	s_ashr_i32 s23, s22, 31
	s_lshl_b64 s[22:23], s[22:23], 3
	s_add_u32 s22, s0, s22
	s_addc_u32 s23, s1, s23
	s_load_dwordx2 s[44:45], s[22:23], 0x0
	s_mul_hi_i32 s23, s34, 0x2aaaaaab
	s_lshr_b32 s46, s23, 31
	s_add_i32 s46, s23, s46
	s_mul_i32 s23, s46, 6
	s_sub_i32 s23, s34, s23
	v_cvt_f32_i32_e32 v0, s23
	s_ashr_i32 s47, s46, 31
	s_lshl_b32 s34, s92, 7
	s_lshl_b64 s[46:47], s[46:47], 13
	v_sub_f32_e32 v0, 0xc0a00000, v0
	v_cmp_gt_f32_e32 vcc, s64, v0
	s_and_b32 s34, s34, 0x1f80
	s_or_b32 s46, s46, s34
	v_cndmask_b32_e32 v2, 0, v241, vcc
	v_add_f32_e32 v0, v0, v2
	v_exp_f32_e32 v0, v0
	s_and_b64 s[50:51], vcc, exec
	s_cselect_b32 s34, 0xffffffc0, 0
	s_mul_hi_u32 s50, s46, 0x3200
	v_ldexp_f32 v0, v0, s34
	s_mul_i32 s34, s47, 0x3200
	s_add_i32 s50, s50, s34
	s_mul_i32 s34, s46, 0x3200
	s_add_u32 s34, s48, s34
	s_addc_u32 s48, s49, s50
	s_lshl_b32 s50, s23, 7
	s_ashr_i32 s51, s50, 31
	s_lshl_b64 s[52:53], s[50:51], 1
	s_add_u32 s23, s34, s52
	s_addc_u32 s34, s48, s53
	v_sub_f32_e32 v11, 1.0, v0
	s_add_u32 s56, s23, 0x1ce00000
	v_lshlrev_b32_e32 v0, 4, v10
	s_addc_u32 s57, s34, 0
	v_and_b32_e32 v0, 0xf0, v0
	v_lshl_add_u64 v[16:17], s[56:57], 0, v[0:1]
	v_ashrrev_i32_e32 v2, 4, v10
	v_mad_i64_i32 v[18:19], s[48:49], v2, s61, v[16:17]
	global_load_dwordx4 v[120:123], v[18:19], off
	v_add_u32_e32 v26, 0, v0
	v_mul_lo_u32 v27, v2, s65
	v_add_u32_e32 v28, v26, v27
	s_ashr_i32 s93, s92, 31
	v_ashrrev_i32_e32 v3, 31, v2
	v_readfirstlane_b32 s22, v10
	v_bfe_u32 v71, v10, 4, 2
	v_lshlrev_b32_e32 v69, 4, v71
	v_add_u32_e32 v4, 0x200, v10
	v_ashrrev_i32_e32 v4, 4, v4
	v_mad_i64_i32 v[20:21], s[48:49], v4, s61, v[16:17]
	global_load_dwordx4 v[124:127], v[20:21], off
	v_mul_lo_u32 v29, v4, s65
	v_add_u32_e32 v30, v26, v29
	v_ashrrev_i32_e32 v5, 31, v4
	v_add_u32_e32 v6, 0x400, v10
	v_ashrrev_i32_e32 v6, 4, v6
	v_mad_i64_i32 v[22:23], s[48:49], v6, s61, v[16:17]
	global_load_dwordx4 v[128:131], v[22:23], off
	v_add_u32_e32 v8, 0x600, v10
	v_mul_lo_u32 v31, v6, s65
	v_ashrrev_i32_e32 v8, 4, v8
	v_add_u32_e32 v32, v26, v31
	v_mad_i64_i32 v[24:25], s[48:49], v8, s61, v[16:17]
	s_lshl_b64 s[48:49], s[92:93], 15
	s_add_u32 s40, s40, s48
	s_addc_u32 s41, s41, s49
	v_ashrrev_i32_e32 v7, 31, v6
	v_ashrrev_i32_e32 v9, 31, v8
	s_ashr_i32 s34, s22, 2
	s_mov_b32 s22, 0x800000
	v_cmp_gt_f32_e32 vcc, s22, v11
	s_and_b64 s[22:23], vcc, exec
	s_cselect_b32 s22, 32, 0
	v_bfi_b32 v66, -16, s34, v10
	global_load_dwordx4 v[132:135], v[24:25], off
	v_mul_lo_u32 v12, v8, s65
	v_add_u32_e32 v13, v26, v12
	v_mov_b32_e32 v119, v13
	global_load_dwordx4 v[136:139], v[18:19], off offset:1536
	global_load_dwordx4 v[140:143], v[20:21], off offset:1536
	global_load_dwordx4 v[144:147], v[22:23], off offset:1536
	global_load_dwordx4 v[148:151], v[24:25], off offset:1536
	v_and_b32_e32 v13, 0x7f, v10
	v_mul_u32_u24_e32 v14, 0x1900, v13
	v_lshlrev_b32_e32 v14, 1, v14
	v_mov_b32_e32 v15, v1
	v_lshl_add_u64 v[18:19], s[56:57], 0, v[14:15]
	v_and_b32_e32 v14, -8, v2
	v_ashrrev_i32_e32 v15, 31, v14
	v_lshl_add_u64 v[16:17], v[14:15], 1, v[18:19]
	v_mul_lo_u32 v14, v14, s65
	v_lshlrev_b32_e32 v13, 1, v13
	v_add3_u32 v20, s70, v14, v13
	global_load_dwordx4 v[152:155], v[16:17], off offset:3072
	v_lshlrev_b64 v[2:3], 8, v[2:3]
	v_mov_b32_e32 v156, v20
	v_and_b32_e32 v14, -8, v4
	v_ashrrev_i32_e32 v15, 31, v14
	v_lshl_add_u64 v[16:17], v[14:15], 1, v[18:19]
	v_mul_lo_u32 v14, v14, s65
	v_add3_u32 v20, s70, v14, v13
	global_load_dwordx4 v[158:161], v[16:17], off offset:3072
	v_mov_b32_e32 v157, v20
	v_and_b32_e32 v14, -8, v6
	v_ashrrev_i32_e32 v15, 31, v14
	v_lshl_add_u64 v[16:17], v[14:15], 1, v[18:19]
	v_mul_lo_u32 v14, v14, s65
	v_add3_u32 v20, s70, v14, v13
	global_load_dwordx4 v[162:165], v[16:17], off offset:3072
	v_and_b32_e32 v14, -8, v8
	v_ashrrev_i32_e32 v15, 31, v14
	v_lshl_add_u64 v[16:17], v[14:15], 1, v[18:19]
	v_mul_lo_u32 v14, v14, s65
	v_add3_u32 v13, s70, v14, v13
	global_load_dwordx4 v[166:169], v[16:17], off offset:3072
	v_mov_b32_e32 v170, v13
	v_lshl_add_u64 v[14:15], s[40:41], 0, v[0:1]
	s_mov_b64 s[40:41], 0x33600000
	v_lshl_add_u64 v[18:19], v[14:15], 0, s[40:41]
	v_lshl_add_u64 v[2:3], v[18:19], 0, v[2:3]
	global_load_dwordx4 v[172:175], v[2:3], off
	v_readlane_b32 s40, v255, 29
	s_nop 1
	v_add_u32_e32 v0, s40, v0
	v_add_u32_e32 v2, v0, v27
	v_add_u32_e32 v13, v0, v29
	v_mov_b32_e32 v171, v2
	v_lshlrev_b64 v[2:3], 8, v[4:5]
	v_lshl_add_u64 v[2:3], v[18:19], 0, v[2:3]
	global_load_dwordx4 v[176:179], v[2:3], off
	v_lshlrev_b64 v[2:3], 8, v[6:7]
	v_lshl_add_u64 v[2:3], v[18:19], 0, v[2:3]
	global_load_dwordx4 v[180:183], v[2:3], off
	v_add_u32_e32 v6, v0, v31
	v_add_u32_e32 v0, v0, v12
	v_lshlrev_b64 v[2:3], 8, v[8:9]
	v_lshl_add_u64 v[2:3], v[18:19], 0, v[2:3]
	global_load_dwordx4 v[184:187], v[2:3], off
	s_waitcnt vmcnt(15)
; #define LAS __attribute__((address_space(3)))
; #define ZERO8(a) do { _Pragma("unroll") for (int t_ = 0; t_ < 8; ++t_) a[t_] = (f32x4){0.f, 0.f, 0.f, 0.f}; } while (0)
; __device__ __forceinline__ void stage_nat(LAS bfu* dst, const bfu* src, int pitch, int tid) {
; #pragma unroll
;     for (int i = 0; i < 4; ++i) { const int id = tid + NTHR * i, r = id >> 4, ch = id & 15; const v4u v = *(const v4u*)(src + (size_t)r * pitch + ch * 8); *(LAS v4u*)(dst + r * TS + ch * 8) = v; }
; __device__ __forceinline__ void ret_unit(LAS unsigned char* lds, const bfu* PROJ, const bfu* RT, const float* gn_g, bfu* CAT, int u) {
;     ...
;     stage_nat(Qs, P0 + C_RQ, INW, tid); stage_nat(Ks, P0 + C_RK, INW, tid); stage_tr<false>(Vt, P0 + C_RV, INW, tid, 0.f); stage_nat(Rt, RT + (size_t)u * 16384, 128, tid);
;     __syncthreads();
;     const int fr = lane & 15, fq = lane >> 4, m0 = wid * 16, c = m0 + fr;
;     f32x4 acc[8], cr[8]; ZERO8(acc); ZERO8(cr);
;     wave_mma(cr, Qs, Rt, m0, fr, fq);
;     wave_mma(acc, Qs, Ks, m0, fr, fq);
	ds_write_b128 v28, v[120:123]
	s_waitcnt vmcnt(14)
	ds_write_b128 v30, v[124:127]
	s_waitcnt vmcnt(13)
	ds_write_b128 v32, v[128:131]
	s_waitcnt vmcnt(12)
	ds_write_b128 v119, v[132:135]
	s_waitcnt vmcnt(11)
	ds_write_b128 v28, v[136:139] offset:34816
	s_waitcnt vmcnt(10)
	ds_write_b128 v30, v[140:143] offset:34816
	s_waitcnt vmcnt(9)
	ds_write_b128 v32, v[144:147] offset:34816
	s_waitcnt vmcnt(8)
	ds_write_b128 v119, v[148:151] offset:34816
	s_waitcnt vmcnt(7)
	ds_write_b16 v156, v152
	ds_write_b16_d16_hi v156, v152 offset:272
	ds_write_b16 v156, v153 offset:544
	ds_write_b16_d16_hi v156, v153 offset:816
	ds_write_b16 v156, v154 offset:1088
	ds_write_b16_d16_hi v156, v154 offset:1360
	ds_write_b16 v156, v155 offset:1632
	ds_write_b16_d16_hi v156, v155 offset:1904
	s_waitcnt vmcnt(6)
	ds_write_b16 v157, v158
	ds_write_b16_d16_hi v157, v158 offset:272
	ds_write_b16 v157, v159 offset:544
	ds_write_b16_d16_hi v157, v159 offset:816
	ds_write_b16 v157, v160 offset:1088
	ds_write_b16_d16_hi v157, v160 offset:1360
	ds_write_b16 v157, v161 offset:1632
	ds_write_b16_d16_hi v157, v161 offset:1904
	s_waitcnt vmcnt(5)
	ds_write_b16 v20, v162
	ds_write_b16_d16_hi v20, v162 offset:272
	ds_write_b16 v20, v163 offset:544
	ds_write_b16_d16_hi v20, v163 offset:816
	ds_write_b16 v20, v164 offset:1088
	ds_write_b16_d16_hi v20, v164 offset:1360
	ds_write_b16 v20, v165 offset:1632
	ds_write_b16_d16_hi v20, v165 offset:1904
	s_waitcnt vmcnt(4)
	ds_write_b16 v170, v166
	ds_write_b16_d16_hi v170, v166 offset:272
	ds_write_b16 v170, v167 offset:544
	ds_write_b16_d16_hi v170, v167 offset:816
	ds_write_b16 v170, v168 offset:1088
	ds_write_b16_d16_hi v170, v168 offset:1360
	ds_write_b16 v170, v169 offset:1632
	ds_write_b16_d16_hi v170, v169 offset:1904
	s_waitcnt vmcnt(3)
	ds_write_b128 v171, v[172:175]
	s_waitcnt vmcnt(2)
	ds_write_b128 v13, v[176:179]
	s_waitcnt vmcnt(1)
	ds_write_b128 v6, v[180:183]
	s_waitcnt vmcnt(0)
	ds_write_b128 v0, v[184:187]
	v_ldexp_f32 v0, v11, s22
	v_log_f32_e32 v0, v0
	v_cndmask_b32_e32 v2, 0, v242, vcc
	s_waitcnt lgkmcnt(0)
	s_barrier
	v_sub_f32_e32 v67, v0, v2
	v_and_b32_e32 v2, 15, v10
	v_mul_lo_u32 v0, v66, s65
	v_add_u32_e32 v73, 0, v0
	v_mul_u32_u24_e32 v70, 0x110, v2
	v_add_u32_e32 v62, v73, v69
	v_add3_u32 v63, s40, v69, v70
	ds_read_b128 v[46:49], v62
	ds_read_b128 v[2:5], v63
	ds_read_b128 v[6:9], v63 offset:4352
	ds_read_b128 v[10:13], v63 offset:8704
	ds_read_b128 v[14:17], v63 offset:13056
	ds_read_b128 v[18:21], v63 offset:17408
	ds_read_b128 v[22:25], v63 offset:21760
	ds_read_b128 v[26:29], v63 offset:26112
	ds_read_b128 v[30:33], v63 offset:30464
	ds_read_b128 v[38:41], v62 offset:64
	ds_read_b128 v[34:37], v63 offset:64
	s_waitcnt lgkmcnt(9)
	v_mfma_f32_16x16x32_bf16 v[2:5], v[2:5], v[46:49], 0
	v_add3_u32 v72, 0, v69, v70
	v_lshlrev_b32_e32 v0, 3, v71
	s_waitcnt lgkmcnt(0)
	v_mfma_f32_16x16x32_bf16 v[2:5], v[34:37], v[38:41], v[2:5]
	ds_read_b128 v[34:37], v63 offset:4416
	v_mfma_f32_16x16x32_bf16 v[6:9], v[6:9], v[46:49], 0
	s_waitcnt lgkmcnt(0)
	v_mfma_f32_16x16x32_bf16 v[6:9], v[34:37], v[38:41], v[6:9]
	ds_read_b128 v[34:37], v63 offset:8768
	v_mfma_f32_16x16x32_bf16 v[10:13], v[10:13], v[46:49], 0
	s_waitcnt lgkmcnt(0)
	v_mfma_f32_16x16x32_bf16 v[10:13], v[34:37], v[38:41], v[10:13]
	ds_read_b128 v[34:37], v63 offset:13120
	v_mfma_f32_16x16x32_bf16 v[14:17], v[14:17], v[46:49], 0
	s_waitcnt lgkmcnt(0)
	v_mfma_f32_16x16x32_bf16 v[14:17], v[34:37], v[38:41], v[14:17]
	ds_read_b128 v[34:37], v63 offset:17472
	v_mfma_f32_16x16x32_bf16 v[18:21], v[18:21], v[46:49], 0
	s_waitcnt lgkmcnt(0)
	v_mfma_f32_16x16x32_bf16 v[18:21], v[34:37], v[38:41], v[18:21]
	ds_read_b128 v[34:37], v63 offset:21824
	v_mfma_f32_16x16x32_bf16 v[22:25], v[22:25], v[46:49], 0
	s_waitcnt lgkmcnt(0)
	v_mfma_f32_16x16x32_bf16 v[22:25], v[34:37], v[38:41], v[22:25]
	ds_read_b128 v[34:37], v63 offset:26176
	v_mfma_f32_16x16x32_bf16 v[26:29], v[26:29], v[46:49], 0
	s_waitcnt lgkmcnt(0)
	v_mfma_f32_16x16x32_bf16 v[26:29], v[34:37], v[38:41], v[26:29]
	ds_read_b128 v[34:37], v63 offset:30528
	v_mfma_f32_16x16x32_bf16 v[30:33], v[30:33], v[46:49], 0
	s_waitcnt lgkmcnt(0)
	v_mfma_f32_16x16x32_bf16 v[30:33], v[34:37], v[38:41], v[30:33]
	ds_read_b128 v[42:45], v62 offset:128
	ds_read_b128 v[34:37], v63 offset:128
	s_waitcnt lgkmcnt(0)
	v_mfma_f32_16x16x32_bf16 v[2:5], v[34:37], v[42:45], v[2:5]
	ds_read_b128 v[34:37], v63 offset:4480
	s_waitcnt lgkmcnt(0)
	v_mfma_f32_16x16x32_bf16 v[6:9], v[34:37], v[42:45], v[6:9]
	ds_read_b128 v[34:37], v63 offset:8832
	s_waitcnt lgkmcnt(0)
	v_mfma_f32_16x16x32_bf16 v[50:53], v[34:37], v[42:45], v[10:13]
	s_nop 2
	ds_read_b128 v[10:13], v63 offset:13184
	s_waitcnt lgkmcnt(0)
	v_mfma_f32_16x16x32_bf16 v[14:17], v[10:13], v[42:45], v[14:17]
	ds_read_b128 v[10:13], v63 offset:17536
	s_waitcnt lgkmcnt(0)
	v_mfma_f32_16x16x32_bf16 v[18:21], v[10:13], v[42:45], v[18:21]
	ds_read_b128 v[10:13], v63 offset:21888
	s_waitcnt lgkmcnt(0)
	v_mfma_f32_16x16x32_bf16 v[22:25], v[10:13], v[42:45], v[22:25]
	ds_read_b128 v[10:13], v63 offset:26240
	s_waitcnt lgkmcnt(0)
	v_mfma_f32_16x16x32_bf16 v[54:57], v[10:13], v[42:45], v[26:29]
	ds_read_b128 v[10:13], v63 offset:30592
	s_waitcnt lgkmcnt(0)
	v_mfma_f32_16x16x32_bf16 v[58:61], v[10:13], v[42:45], v[30:33]
	ds_read_b128 v[34:37], v62 offset:192
	ds_read_b128 v[10:13], v63 offset:192
	ds_read_b128 v[74:77], v72 offset:52224
	ds_read_b128 v[78:81], v72 offset:56576
	ds_read_b128 v[82:85], v72 offset:60928
	s_waitcnt lgkmcnt(3)
	v_mfma_f32_16x16x32_bf16 v[10:13], v[10:13], v[34:37], v[2:5]
	ds_read_b128 v[86:89], v72 offset:65280
	s_nop 1
	ds_read_b128 v[2:5], v63 offset:4544
	s_waitcnt lgkmcnt(0)
; __device__ __forceinline__ float fexp2(float x) { return __builtin_amdgcn_exp2f(x); }
; __device__ __forceinline__ void ret_unit(LAS unsigned char* lds, const bfu* PROJ, const bfu* RT, const float* gn_g, bfu* CAT, int u) {
;     ...
;     wave_mma(cr, Qs, Rt, m0, fr, fq);
;     wave_mma(acc, Qs, Ks, m0, fr, fq);
;     __syncthreads();
; #pragma unroll
;     for (int t = 0; t < 8; ++t) { float p[4];
; #pragma unroll
;         for (int j = 0; j < 4; ++j) { const int e = 16 * t + 4 * fq + j; p[j] = (c >= e) ? acc[t][j] * fexp2(lg * (float)(c - e)) : 0.f; }
	v_mfma_f32_16x16x32_bf16 v[30:33], v[2:5], v[34:37], v[6:9]
	ds_read_b128 v[2:5], v63 offset:8896
	s_nop 1
	ds_read_b128 v[6:9], v63 offset:13248
	s_waitcnt lgkmcnt(0)
	v_mfma_f32_16x16x32_bf16 v[14:17], v[6:9], v[34:37], v[14:17]
	ds_read_b128 v[6:9], v63 offset:17600
	v_mfma_f32_16x16x32_bf16 v[2:5], v[2:5], v[34:37], v[50:53]
	s_nop 2
	ds_read_b128 v[50:53], v72 offset:34816
	s_waitcnt lgkmcnt(1)
	v_mfma_f32_16x16x32_bf16 v[26:29], v[6:9], v[34:37], v[18:21]
	ds_read_b128 v[6:9], v63 offset:21952
	s_nop 1
	ds_read_b128 v[18:21], v63 offset:26304
	s_waitcnt lgkmcnt(1)
	v_mfma_f32_16x16x32_bf16 v[6:9], v[6:9], v[34:37], v[22:25]
	s_nop 2
	ds_read_b128 v[22:25], v63 offset:30656
	s_waitcnt lgkmcnt(1)
	v_mfma_f32_16x16x32_bf16 v[18:21], v[18:21], v[34:37], v[54:57]
	s_nop 2
	ds_read_b128 v[54:57], v72 offset:39168
	s_waitcnt lgkmcnt(1)
	v_mfma_f32_16x16x32_bf16 v[22:25], v[22:25], v[34:37], v[58:61]
	ds_read_b128 v[62:65], v72 offset:47872
	s_nop 1
	ds_read_b128 v[58:61], v72 offset:43520
	v_mfma_f32_16x16x32_bf16 v[50:53], v[50:53], v[46:49], 0
	s_waitcnt lgkmcnt(2)
	v_mfma_f32_16x16x32_bf16 v[54:57], v[54:57], v[46:49], 0
	s_waitcnt lgkmcnt(0)
	v_mfma_f32_16x16x32_bf16 v[58:61], v[58:61], v[46:49], 0
	v_mfma_f32_16x16x32_bf16 v[62:65], v[62:65], v[46:49], 0
	v_mfma_f32_16x16x32_bf16 v[74:77], v[74:77], v[46:49], 0
	v_mfma_f32_16x16x32_bf16 v[78:81], v[78:81], v[46:49], 0
	v_mfma_f32_16x16x32_bf16 v[82:85], v[82:85], v[46:49], 0
	v_mfma_f32_16x16x32_bf16 v[46:49], v[86:89], v[46:49], 0
	ds_read_b128 v[86:89], v72 offset:34880
	s_waitcnt lgkmcnt(0)
	v_mfma_f32_16x16x32_bf16 v[50:53], v[86:89], v[38:41], v[50:53]
	ds_read_b128 v[86:89], v72 offset:39232
	s_waitcnt lgkmcnt(0)
	v_mfma_f32_16x16x32_bf16 v[54:57], v[86:89], v[38:41], v[54:57]
	ds_read_b128 v[86:89], v72 offset:43584
	s_waitcnt lgkmcnt(0)
	v_mfma_f32_16x16x32_bf16 v[58:61], v[86:89], v[38:41], v[58:61]
	ds_read_b128 v[86:89], v72 offset:47936
	s_waitcnt lgkmcnt(0)
	v_mfma_f32_16x16x32_bf16 v[62:65], v[86:89], v[38:41], v[62:65]
	ds_read_b128 v[86:89], v72 offset:52288
	s_waitcnt lgkmcnt(0)
	v_mfma_f32_16x16x32_bf16 v[74:77], v[86:89], v[38:41], v[74:77]
	ds_read_b128 v[86:89], v72 offset:56640
	s_waitcnt lgkmcnt(0)
	v_mfma_f32_16x16x32_bf16 v[78:81], v[86:89], v[38:41], v[78:81]
	ds_read_b128 v[86:89], v72 offset:60992
	s_waitcnt lgkmcnt(0)
	v_mfma_f32_16x16x32_bf16 v[82:85], v[86:89], v[38:41], v[82:85]
	ds_read_b128 v[86:89], v72 offset:65344
	s_waitcnt lgkmcnt(0)
	v_mfma_f32_16x16x32_bf16 v[38:41], v[86:89], v[38:41], v[46:49]
	s_nop 2
	ds_read_b128 v[46:49], v72 offset:34944
	s_waitcnt lgkmcnt(0)
	v_mfma_f32_16x16x32_bf16 v[46:49], v[46:49], v[42:45], v[50:53]
	s_nop 2
	ds_read_b128 v[50:53], v72 offset:39296
	s_waitcnt lgkmcnt(0)
	v_mfma_f32_16x16x32_bf16 v[50:53], v[50:53], v[42:45], v[54:57]
	s_nop 2
	ds_read_b128 v[54:57], v72 offset:43648
	s_waitcnt lgkmcnt(0)
	v_mfma_f32_16x16x32_bf16 v[54:57], v[54:57], v[42:45], v[58:61]
	s_nop 2
	ds_read_b128 v[58:61], v72 offset:48000
	s_waitcnt lgkmcnt(0)
	v_mfma_f32_16x16x32_bf16 v[86:89], v[58:61], v[42:45], v[62:65]
	ds_read_b128 v[58:61], v72 offset:52352
	s_waitcnt lgkmcnt(0)
	v_mfma_f32_16x16x32_bf16 v[74:77], v[58:61], v[42:45], v[74:77]
	ds_read_b128 v[58:61], v72 offset:56704
	s_waitcnt lgkmcnt(0)
	v_mfma_f32_16x16x32_bf16 v[78:81], v[58:61], v[42:45], v[78:81]
	ds_read_b128 v[58:61], v72 offset:61056
	s_waitcnt lgkmcnt(0)
	v_mfma_f32_16x16x32_bf16 v[82:85], v[58:61], v[42:45], v[82:85]
	ds_read_b128 v[58:61], v72 offset:65408
	s_waitcnt lgkmcnt(0)
	v_mfma_f32_16x16x32_bf16 v[90:93], v[58:61], v[42:45], v[38:41]
	s_nop 2
	ds_read_b128 v[38:41], v72 offset:35008
	s_waitcnt lgkmcnt(0)
	v_mfma_f32_16x16x32_bf16 v[62:65], v[38:41], v[34:37], v[46:49]
	ds_read_b128 v[38:41], v72 offset:39360
	s_waitcnt lgkmcnt(0)
	v_mfma_f32_16x16x32_bf16 v[58:61], v[38:41], v[34:37], v[50:53]
	ds_read_b128 v[38:41], v72 offset:43712
	s_waitcnt lgkmcnt(0)
	v_mfma_f32_16x16x32_bf16 v[54:57], v[38:41], v[34:37], v[54:57]
	ds_read_b128 v[38:41], v72 offset:48064
	s_waitcnt lgkmcnt(0)
	v_mfma_f32_16x16x32_bf16 v[50:53], v[38:41], v[34:37], v[86:89]
	ds_read_b128 v[38:41], v72 offset:52416
	s_waitcnt lgkmcnt(0)
	v_mfma_f32_16x16x32_bf16 v[46:49], v[38:41], v[34:37], v[74:77]
	ds_read_b128 v[38:41], v72 offset:56768
	s_nop 1
	ds_read_b128 v[74:77], v72 offset:65472
	s_waitcnt lgkmcnt(1)
	v_mfma_f32_16x16x32_bf16 v[42:45], v[38:41], v[34:37], v[78:81]
	ds_read_b128 v[38:41], v72 offset:61120
	v_lshlrev_b32_e32 v72, 2, v71
	v_add_u32_e32 v71, v73, v0
	v_sub_u32_e32 v73, v66, v72
	v_cvt_f32_i32_e32 v73, v73
	v_cmp_ge_i32_e32 vcc, v66, v72
	s_waitcnt lgkmcnt(0)
	v_mfma_f32_16x16x32_bf16 v[38:41], v[38:41], v[34:37], v[82:85]
	v_mul_f32_e32 v73, v67, v73
	v_exp_f32_e32 v73, v73
	v_mfma_f32_16x16x32_bf16 v[34:37], v[74:77], v[34:37], v[90:93]
	v_or_b32_e32 v75, 3, v72
	v_mul_f32_e32 v62, v73, v62
	v_cndmask_b32_e32 v73, 0, v62, vcc
	v_xad_u32 v62, v72, -1, v66
	v_cvt_f32_i32_e32 v62, v62
	v_cmp_gt_i32_e32 vcc, v66, v72
	v_or_b32_e32 v76, 2, v72
	s_barrier
; #define LAS __attribute__((address_space(3)))
; __device__ __forceinline__ unsigned pk2(float lo, float hi) { return pg8::cvt_pk_bf16(lo, hi); }
; __device__ __forceinline__ float fexp2(float x) { return __builtin_amdgcn_exp2f(x); }
; __device__ __forceinline__ void ret_unit(LAS unsigned char* lds, const bfu* PROJ, const bfu* RT, const float* gn_g, bfu* CAT, int u) {
;     ...
;     for (int t = 0; t < 8; ++t) { float p[4];
; #pragma unroll
;         for (int j = 0; j < 4; ++j) { const int e = 16 * t + 4 * fq + j; p[j] = (c >= e) ? acc[t][j] * fexp2(lg * (float)(c - e)) : 0.f; }
;         v2u w; w.x = pk2(p[0], p[1]); w.y = pk2(p[2], p[3]); *(LAS v2u*)(Ks + c * TS + 16 * t + 4 * fq) = w; }
	v_mul_f32_e32 v62, v67, v62
	v_exp_f32_e32 v62, v62
	v_add_u32_e32 v78, v71, v0
	v_add3_u32 v82, s70, v69, v70
	v_mul_f32_e32 v62, v62, v63
	v_cndmask_b32_e32 v74, 0, v62, vcc
	v_sub_u32_e32 v62, v66, v76
	v_sub_u32_e32 v63, v66, v75
	v_cvt_f32_i32_e32 v62, v62
	v_cvt_f32_i32_e32 v63, v63
	v_cmp_ge_i32_e32 vcc, v66, v76
	v_or_b32_e32 v76, 18, v72
	v_mul_f32_e32 v62, v67, v62
	v_mul_f32_e32 v63, v67, v63
	v_exp_f32_e32 v62, v62
	v_exp_f32_e32 v63, v63
	s_nop 0
	v_pk_mul_f32 v[62:63], v[62:63], v[64:65]
	s_nop 0
	v_cvt_pk_bf16_f32 v62, v62, v63
	v_cndmask_b32_e32 v63, 0, v62, vcc
	v_lshrrev_b32_e32 v62, 16, v62
	v_cmp_ge_i32_e32 vcc, v66, v75
	v_cvt_pk_bf16_f32 v64, v73, v74
	v_or_b32_e32 v73, 17, v72
	v_cndmask_b32_e32 v62, 0, v62, vcc
	v_or_b32_e32 v74, 16, v72
	v_perm_b32 v65, v62, v63, s72
	v_sub_u32_e32 v62, v66, v74
	v_sub_u32_e32 v63, v66, v73
	v_cvt_f32_i32_e32 v62, v62
	v_cvt_f32_i32_e32 v63, v63
	v_or_b32_e32 v75, 19, v72
	v_cmp_ge_i32_e32 vcc, v66, v74
	v_mul_f32_e32 v62, v67, v62
	v_mul_f32_e32 v63, v67, v63
	v_exp_f32_e32 v62, v62
	v_exp_f32_e32 v63, v63
	s_nop 0
	v_pk_mul_f32 v[58:59], v[62:63], v[58:59]
	v_sub_u32_e32 v62, v66, v76
	v_sub_u32_e32 v63, v66, v75
	v_cvt_f32_i32_e32 v62, v62
	v_cvt_f32_i32_e32 v63, v63
	v_cvt_pk_bf16_f32 v58, v58, v59
	v_cndmask_b32_e32 v59, 0, v58, vcc
	v_mul_f32_e32 v62, v67, v62
	v_mul_f32_e32 v63, v67, v63
	v_exp_f32_e32 v62, v62
	v_exp_f32_e32 v63, v63
	v_lshrrev_b32_e32 v58, 16, v58
	v_cmp_ge_i32_e32 vcc, v66, v73
	v_pk_mul_f32 v[60:61], v[62:63], v[60:61]
	s_nop 0
	v_cndmask_b32_e32 v58, 0, v58, vcc
	v_perm_b32 v62, v58, v59, s72
	v_cvt_pk_bf16_f32 v58, v60, v61
	v_cmp_ge_i32_e32 vcc, v66, v76
	s_nop 1
	v_cndmask_b32_e32 v59, 0, v58, vcc
	v_lshrrev_b32_e32 v58, 16, v58
	v_cmp_ge_i32_e32 vcc, v66, v75
	s_nop 1
	v_cndmask_b32_e32 v58, 0, v58, vcc
	v_perm_b32 v63, v58, v59, s72
	v_add_u32_e32 v58, 0x8800, v71
	ds_write2_b64 v58, v[64:65], v[62:63] offset1:4
	v_or_b32_e32 v59, 33, v72
	v_or_b32_e32 v62, 32, v72
	v_sub_u32_e32 v60, v66, v62
	v_sub_u32_e32 v61, v66, v59
	v_cvt_f32_i32_e32 v60, v60
	v_cvt_f32_i32_e32 v61, v61
	v_or_b32_e32 v63, 35, v72
	v_or_b32_e32 v64, 34, v72
	v_mul_f32_e32 v60, v67, v60
	v_mul_f32_e32 v61, v67, v61
	v_exp_f32_e32 v60, v60
	v_exp_f32_e32 v61, v61
	v_cmp_ge_i32_e32 vcc, v66, v62
	v_or_b32_e32 v62, 50, v72
	v_pk_mul_f32 v[54:55], v[60:61], v[54:55]
	v_sub_u32_e32 v60, v66, v64
	v_sub_u32_e32 v61, v66, v63
	v_cvt_f32_i32_e32 v60, v60
	v_cvt_f32_i32_e32 v61, v61
	v_cvt_pk_bf16_f32 v54, v54, v55
	v_cndmask_b32_e32 v55, 0, v54, vcc
	v_mul_f32_e32 v60, v67, v60
	v_mul_f32_e32 v61, v67, v61
	v_exp_f32_e32 v60, v60
	v_exp_f32_e32 v61, v61
	v_lshrrev_b32_e32 v54, 16, v54
	v_cmp_ge_i32_e32 vcc, v66, v59
	v_or_b32_e32 v59, 49, v72
	v_pk_mul_f32 v[56:57], v[60:61], v[56:57]
	v_cndmask_b32_e32 v54, 0, v54, vcc
	v_perm_b32 v54, v54, v55, s72
	v_cvt_pk_bf16_f32 v55, v56, v57
	v_cmp_ge_i32_e32 vcc, v66, v64
	v_or_b32_e32 v60, 48, v72
	v_sub_u32_e32 v57, v66, v59
	v_cndmask_b32_e32 v56, 0, v55, vcc
	v_lshrrev_b32_e32 v55, 16, v55
	v_cmp_ge_i32_e32 vcc, v66, v63
	v_cvt_f32_i32_e32 v57, v57
	v_or_b32_e32 v61, 51, v72
	v_cndmask_b32_e32 v55, 0, v55, vcc
	v_perm_b32 v55, v55, v56, s72
	v_sub_u32_e32 v56, v66, v60
	v_cvt_f32_i32_e32 v56, v56
	v_mul_f32_e32 v57, v67, v57
	v_exp_f32_e32 v57, v57
	v_cmp_ge_i32_e32 vcc, v66, v60
	v_mul_f32_e32 v56, v67, v56
	v_exp_f32_e32 v56, v56
	s_nop 0
	v_pk_mul_f32 v[50:51], v[56:57], v[50:51]
	v_sub_u32_e32 v56, v66, v62
	v_sub_u32_e32 v57, v66, v61
	v_cvt_f32_i32_e32 v56, v56
	v_cvt_f32_i32_e32 v57, v57
	v_cvt_pk_bf16_f32 v50, v50, v51
	v_cndmask_b32_e32 v51, 0, v50, vcc
	v_mul_f32_e32 v56, v67, v56
	v_mul_f32_e32 v57, v67, v57
	v_exp_f32_e32 v56, v56
	v_exp_f32_e32 v57, v57
	v_lshrrev_b32_e32 v50, 16, v50
	v_cmp_ge_i32_e32 vcc, v66, v59
	v_pk_mul_f32 v[52:53], v[56:57], v[52:53]
	s_nop 0
	v_cndmask_b32_e32 v50, 0, v50, vcc
	v_perm_b32 v50, v50, v51, s72
	v_cvt_pk_bf16_f32 v51, v52, v53
	v_cmp_ge_i32_e32 vcc, v66, v62
	v_or_b32_e32 v53, 64, v72
	s_nop 0
	v_cndmask_b32_e32 v52, 0, v51, vcc
	v_lshrrev_b32_e32 v51, 16, v51
	v_cmp_ge_i32_e32 vcc, v66, v61
	s_nop 1
	v_cndmask_b32_e32 v51, 0, v51, vcc
	v_perm_b32 v51, v51, v52, s72
	v_or_b32_e32 v52, 0x41, v72
	ds_write2_b64 v58, v[54:55], v[50:51] offset0:8 offset1:12
	v_sub_u32_e32 v50, v66, v53
	v_sub_u32_e32 v51, v66, v52
	v_cvt_f32_i32_e32 v50, v50
	v_cvt_f32_i32_e32 v51, v51
	v_or_b32_e32 v54, 0x43, v72
	v_or_b32_e32 v55, 0x42, v72
	v_mul_f32_e32 v50, v67, v50
	v_mul_f32_e32 v51, v67, v51
	v_exp_f32_e32 v50, v50
	v_exp_f32_e32 v51, v51
	v_cmp_ge_i32_e32 vcc, v66, v53
	v_or_b32_e32 v53, 0x52, v72
	v_pk_mul_f32 v[46:47], v[50:51], v[46:47]
	v_sub_u32_e32 v50, v66, v55
	v_sub_u32_e32 v51, v66, v54
	v_cvt_f32_i32_e32 v50, v50
	v_cvt_f32_i32_e32 v51, v51
	v_cvt_pk_bf16_f32 v46, v46, v47
	v_cndmask_b32_e32 v47, 0, v46, vcc
	v_mul_f32_e32 v50, v67, v50
	v_mul_f32_e32 v51, v67, v51
	v_exp_f32_e32 v50, v50
	v_exp_f32_e32 v51, v51
	v_lshrrev_b32_e32 v46, 16, v46
	v_cmp_ge_i32_e32 vcc, v66, v52
	v_or_b32_e32 v52, 0x53, v72
	v_pk_mul_f32 v[48:49], v[50:51], v[48:49]
	v_cndmask_b32_e32 v46, 0, v46, vcc
	v_perm_b32 v46, v46, v47, s72
	v_cvt_pk_bf16_f32 v47, v48, v49
	v_cmp_ge_i32_e32 vcc, v66, v55
	v_or_b32_e32 v50, 0x51, v72
	v_or_b32_e32 v51, 0x50, v72
	v_cndmask_b32_e32 v48, 0, v47, vcc
	v_lshrrev_b32_e32 v47, 16, v47
	v_cmp_ge_i32_e32 vcc, v66, v54
	v_sub_u32_e32 v49, v66, v50
	v_cvt_f32_i32_e32 v49, v49
	v_cndmask_b32_e32 v47, 0, v47, vcc
	v_perm_b32 v47, v47, v48, s72
	v_sub_u32_e32 v48, v66, v51
	v_cvt_f32_i32_e32 v48, v48
	v_mul_f32_e32 v49, v67, v49
	v_exp_f32_e32 v49, v49
	v_cmp_ge_i32_e32 vcc, v66, v51
; #define LAS __attribute__((address_space(3)))
; #define LDS_WAIT() asm volatile("s_waitcnt lgkmcnt(0)" ::: "memory")
; __device__ __forceinline__ unsigned pk2(float lo, float hi) { return pg8::cvt_pk_bf16(lo, hi); }
; __device__ __forceinline__ float fexp2(float x) { return __builtin_amdgcn_exp2f(x); }
; #define ZERO8(a) do { _Pragma("unroll") for (int t_ = 0; t_ < 8; ++t_) a[t_] = (f32x4){0.f, 0.f, 0.f, 0.f}; } while (0)
; __device__ __forceinline__ void ret_unit(LAS unsigned char* lds, const bfu* PROJ, const bfu* RT, const float* gn_g, bfu* CAT, int u) {
;     ...
;     for (int t = 0; t < 8; ++t) { float p[4];
; #pragma unroll
;         for (int j = 0; j < 4; ++j) { const int e = 16 * t + 4 * fq + j; p[j] = (c >= e) ? acc[t][j] * fexp2(lg * (float)(c - e)) : 0.f; }
;         v2u w; w.x = pk2(p[0], p[1]); w.y = pk2(p[2], p[3]); *(LAS v2u*)(Ks + c * TS + 16 * t + 4 * fq) = w; }
;     LDS_WAIT(); asm volatile("" ::: "memory");
;     ZERO8(acc);
;     wave_mma(acc, Ks, Vt, m0, fr, fq);
	v_mul_f32_e32 v48, v67, v48
	v_exp_f32_e32 v48, v48
	s_nop 0
	v_pk_mul_f32 v[42:43], v[48:49], v[42:43]
	v_sub_u32_e32 v48, v66, v53
	v_sub_u32_e32 v49, v66, v52
	v_cvt_f32_i32_e32 v48, v48
	v_cvt_f32_i32_e32 v49, v49
	v_cvt_pk_bf16_f32 v42, v42, v43
	v_cndmask_b32_e32 v43, 0, v42, vcc
	v_mul_f32_e32 v48, v67, v48
	v_mul_f32_e32 v49, v67, v49
	v_exp_f32_e32 v48, v48
	v_exp_f32_e32 v49, v49
	v_lshrrev_b32_e32 v42, 16, v42
	v_cmp_ge_i32_e32 vcc, v66, v50
	v_pk_mul_f32 v[44:45], v[48:49], v[44:45]
	s_nop 0
	v_cndmask_b32_e32 v42, 0, v42, vcc
	v_perm_b32 v42, v42, v43, s72
	v_cvt_pk_bf16_f32 v43, v44, v45
	v_cmp_ge_i32_e32 vcc, v66, v53
	v_or_b32_e32 v45, 0x60, v72
	s_nop 0
	v_cndmask_b32_e32 v44, 0, v43, vcc
	v_lshrrev_b32_e32 v43, 16, v43
	v_cmp_ge_i32_e32 vcc, v66, v52
	s_nop 1
	v_cndmask_b32_e32 v43, 0, v43, vcc
	v_perm_b32 v43, v43, v44, s72
	v_or_b32_e32 v44, 0x61, v72
	ds_write2_b64 v58, v[46:47], v[42:43] offset0:16 offset1:20
	v_sub_u32_e32 v42, v66, v45
	v_sub_u32_e32 v43, v66, v44
	v_cvt_f32_i32_e32 v42, v42
	v_cvt_f32_i32_e32 v43, v43
	v_or_b32_e32 v46, 0x63, v72
	v_or_b32_e32 v47, 0x62, v72
	v_mul_f32_e32 v42, v67, v42
	v_mul_f32_e32 v43, v67, v43
	v_exp_f32_e32 v42, v42
	v_exp_f32_e32 v43, v43
	v_cmp_ge_i32_e32 vcc, v66, v45
	v_or_b32_e32 v45, 0x72, v72
	v_pk_mul_f32 v[38:39], v[42:43], v[38:39]
	v_sub_u32_e32 v42, v66, v47
	v_sub_u32_e32 v43, v66, v46
	v_cvt_f32_i32_e32 v42, v42
	v_cvt_f32_i32_e32 v43, v43
	v_cvt_pk_bf16_f32 v38, v38, v39
	v_cndmask_b32_e32 v39, 0, v38, vcc
	v_mul_f32_e32 v42, v67, v42
	v_mul_f32_e32 v43, v67, v43
	v_exp_f32_e32 v42, v42
	v_exp_f32_e32 v43, v43
	v_lshrrev_b32_e32 v38, 16, v38
	v_cmp_ge_i32_e32 vcc, v66, v44
	v_or_b32_e32 v44, 0x73, v72
	v_pk_mul_f32 v[40:41], v[42:43], v[40:41]
	v_cndmask_b32_e32 v38, 0, v38, vcc
	v_perm_b32 v38, v38, v39, s72
	v_cvt_pk_bf16_f32 v39, v40, v41
	v_cmp_ge_i32_e32 vcc, v66, v47
	v_or_b32_e32 v42, 0x71, v72
	v_or_b32_e32 v43, 0x70, v72
	v_cndmask_b32_e32 v40, 0, v39, vcc
	v_lshrrev_b32_e32 v39, 16, v39
	v_cmp_ge_i32_e32 vcc, v66, v46
	v_sub_u32_e32 v41, v66, v42
	v_cvt_f32_i32_e32 v41, v41
	v_cndmask_b32_e32 v39, 0, v39, vcc
	v_perm_b32 v39, v39, v40, s72
	v_sub_u32_e32 v40, v66, v43
	v_cvt_f32_i32_e32 v40, v40
	v_mul_f32_e32 v41, v67, v41
	v_exp_f32_e32 v41, v41
	v_cmp_ge_i32_e32 vcc, v66, v43
	v_mul_f32_e32 v40, v67, v40
	v_exp_f32_e32 v40, v40
	s_nop 0
	v_pk_mul_f32 v[34:35], v[40:41], v[34:35]
	v_sub_u32_e32 v40, v66, v45
	v_sub_u32_e32 v41, v66, v44
	v_cvt_f32_i32_e32 v40, v40
	v_cvt_f32_i32_e32 v41, v41
	v_cvt_pk_bf16_f32 v34, v34, v35
	v_cndmask_b32_e32 v35, 0, v34, vcc
	v_mul_f32_e32 v40, v67, v40
	v_mul_f32_e32 v41, v67, v41
	v_exp_f32_e32 v40, v40
	v_exp_f32_e32 v41, v41
	v_lshrrev_b32_e32 v34, 16, v34
	v_cmp_ge_i32_e32 vcc, v66, v42
	v_pk_mul_f32 v[36:37], v[40:41], v[36:37]
	s_nop 0
	v_cndmask_b32_e32 v34, 0, v34, vcc
	v_perm_b32 v34, v34, v35, s72
	v_cvt_pk_bf16_f32 v35, v36, v37
	v_cmp_ge_i32_e32 vcc, v66, v45
	s_nop 1
	v_cndmask_b32_e32 v36, 0, v35, vcc
	v_lshrrev_b32_e32 v35, 16, v35
	v_cmp_ge_i32_e32 vcc, v66, v44
	s_nop 1
	v_cndmask_b32_e32 v35, 0, v35, vcc
	v_perm_b32 v35, v35, v36, s72
	ds_write2_b64 v58, v[38:39], v[34:35] offset0:24 offset1:28
	s_waitcnt lgkmcnt(0)
	ds_read_b128 v[34:37], v78 offset:34816
	ds_read_b128 v[38:41], v82
	ds_read_b128 v[42:45], v82 offset:4352
	ds_read_b128 v[46:49], v82 offset:8704
	ds_read_b128 v[50:53], v82 offset:13056
	ds_read_b128 v[54:57], v82 offset:17408
	ds_read_b128 v[58:61], v82 offset:21760
	ds_read_b128 v[62:65], v82 offset:26112
	ds_read_b128 v[70:73], v82 offset:30464
	s_waitcnt lgkmcnt(7)
	v_mfma_f32_16x16x32_bf16 v[38:41], v[38:41], v[34:37], 0
	s_waitcnt lgkmcnt(6)
	v_mfma_f32_16x16x32_bf16 v[42:45], v[42:45], v[34:37], 0
	s_waitcnt lgkmcnt(5)
	v_mfma_f32_16x16x32_bf16 v[46:49], v[46:49], v[34:37], 0
	s_waitcnt lgkmcnt(4)
	v_mfma_f32_16x16x32_bf16 v[50:53], v[50:53], v[34:37], 0
	s_waitcnt lgkmcnt(3)
	v_mfma_f32_16x16x32_bf16 v[54:57], v[54:57], v[34:37], 0
	s_waitcnt lgkmcnt(2)
	v_mfma_f32_16x16x32_bf16 v[58:61], v[58:61], v[34:37], 0
	s_waitcnt lgkmcnt(1)
	v_mfma_f32_16x16x32_bf16 v[62:65], v[62:65], v[34:37], 0
	s_waitcnt lgkmcnt(0)
	v_mfma_f32_16x16x32_bf16 v[34:37], v[70:73], v[34:37], 0
	ds_read_b128 v[70:73], v78 offset:34880
	ds_read_b128 v[74:77], v82 offset:64
	s_waitcnt lgkmcnt(0)
	v_mfma_f32_16x16x32_bf16 v[38:41], v[74:77], v[70:73], v[38:41]
	ds_read_b128 v[74:77], v82 offset:4416
	s_waitcnt lgkmcnt(0)
	v_mfma_f32_16x16x32_bf16 v[42:45], v[74:77], v[70:73], v[42:45]
	ds_read_b128 v[74:77], v82 offset:8768
	s_waitcnt lgkmcnt(0)
	v_mfma_f32_16x16x32_bf16 v[46:49], v[74:77], v[70:73], v[46:49]
	ds_read_b128 v[74:77], v82 offset:13120
	s_waitcnt lgkmcnt(0)
	v_mfma_f32_16x16x32_bf16 v[50:53], v[74:77], v[70:73], v[50:53]
	ds_read_b128 v[74:77], v82 offset:17472
	s_waitcnt lgkmcnt(0)
	v_mfma_f32_16x16x32_bf16 v[54:57], v[74:77], v[70:73], v[54:57]
	ds_read_b128 v[74:77], v82 offset:21824
	s_waitcnt lgkmcnt(0)
	v_mfma_f32_16x16x32_bf16 v[58:61], v[74:77], v[70:73], v[58:61]
	ds_read_b128 v[74:77], v82 offset:26176
	s_waitcnt lgkmcnt(0)
	v_mfma_f32_16x16x32_bf16 v[62:65], v[74:77], v[70:73], v[62:65]
	ds_read_b128 v[74:77], v82 offset:30528
	s_waitcnt lgkmcnt(0)
	v_mfma_f32_16x16x32_bf16 v[34:37], v[74:77], v[70:73], v[34:37]
	ds_read_b128 v[70:73], v78 offset:34944
	ds_read_b128 v[74:77], v82 offset:128
	s_waitcnt lgkmcnt(0)
	v_mfma_f32_16x16x32_bf16 v[38:41], v[74:77], v[70:73], v[38:41]
	ds_read_b128 v[74:77], v82 offset:4480
	s_waitcnt lgkmcnt(0)
	v_mfma_f32_16x16x32_bf16 v[42:45], v[74:77], v[70:73], v[42:45]
	ds_read_b128 v[74:77], v82 offset:8832
	s_waitcnt lgkmcnt(0)
; __device__ __forceinline__ float fexp2(float x) { return __builtin_amdgcn_exp2f(x); }
; __device__ __forceinline__ void ret_unit(LAS unsigned char* lds, const bfu* PROJ, const bfu* RT, const float* gn_g, bfu* CAT, int u) {
;     ...
;     wave_mma(acc, Ks, Vt, m0, fr, fq);
;     const float xi = fexp2(lg * (float)(c + 1)); float s = 0.f;
; #pragma unroll
;     for (int t = 0; t < 8; ++t) { acc[t] = acc[t] + cr[t] * xi; s += (acc[t][0] + acc[t][1]) + (acc[t][2] + acc[t][3]); }
;     s += __shfl_xor(s, 16); s += __shfl_xor(s, 32); const float mu = s * (1.f / 128.f); float q = 0.f;
	v_mfma_f32_16x16x32_bf16 v[46:49], v[74:77], v[70:73], v[46:49]
	ds_read_b128 v[74:77], v82 offset:13184
	s_waitcnt lgkmcnt(0)
	v_mfma_f32_16x16x32_bf16 v[50:53], v[74:77], v[70:73], v[50:53]
	ds_read_b128 v[74:77], v82 offset:17536
	s_waitcnt lgkmcnt(0)
	v_mfma_f32_16x16x32_bf16 v[54:57], v[74:77], v[70:73], v[54:57]
	ds_read_b128 v[74:77], v82 offset:21888
	s_waitcnt lgkmcnt(0)
	v_mfma_f32_16x16x32_bf16 v[58:61], v[74:77], v[70:73], v[58:61]
	ds_read_b128 v[74:77], v82 offset:26240
	s_waitcnt lgkmcnt(0)
	v_mfma_f32_16x16x32_bf16 v[62:65], v[74:77], v[70:73], v[62:65]
	ds_read_b128 v[74:77], v82 offset:30592
	s_waitcnt lgkmcnt(0)
	v_mfma_f32_16x16x32_bf16 v[34:37], v[74:77], v[70:73], v[34:37]
	ds_read_b128 v[70:73], v78 offset:35008
	ds_read_b128 v[74:77], v82 offset:192
	s_waitcnt lgkmcnt(0)
	v_mfma_f32_16x16x32_bf16 v[38:41], v[74:77], v[70:73], v[38:41]
	ds_read_b128 v[74:77], v82 offset:4544
	s_waitcnt lgkmcnt(0)
	v_mfma_f32_16x16x32_bf16 v[74:77], v[74:77], v[70:73], v[42:45]
	s_nop 2
	ds_read_b128 v[42:45], v82 offset:8896
	s_waitcnt lgkmcnt(0)
	v_mfma_f32_16x16x32_bf16 v[78:81], v[42:45], v[70:73], v[46:49]
	ds_read_b128 v[42:45], v82 offset:13248
	s_waitcnt lgkmcnt(0)
	v_mfma_f32_16x16x32_bf16 v[48:51], v[42:45], v[70:73], v[50:53]
	ds_read_b128 v[42:45], v82 offset:17600
	s_waitcnt lgkmcnt(0)
	v_mfma_f32_16x16x32_bf16 v[52:55], v[42:45], v[70:73], v[54:57]
	ds_read_b128 v[42:45], v82 offset:21952
	s_waitcnt lgkmcnt(0)
	v_mfma_f32_16x16x32_bf16 v[56:59], v[42:45], v[70:73], v[58:61]
	ds_read_b128 v[42:45], v82 offset:26304
	s_waitcnt lgkmcnt(0)
	v_mfma_f32_16x16x32_bf16 v[60:63], v[42:45], v[70:73], v[62:65]
	ds_read_b128 v[42:45], v82 offset:30656
	s_waitcnt lgkmcnt(0)
	v_mfma_f32_16x16x32_bf16 v[70:73], v[42:45], v[70:73], v[34:37]
	s_nop 2
	v_add_u32_e32 v34, 1, v66
	v_cvt_f32_i32_e32 v34, v34
	v_mul_f32_e32 v34, v67, v34
	v_exp_f32_e32 v64, v34
	v_ashrrev_i32_e32 v67, 31, v66
	v_pk_fma_f32 v[46:47], v[64:65], v[10:11], v[38:39] op_sel_hi:[0,1,1]
	v_pk_fma_f32 v[42:43], v[64:65], v[30:31], v[74:75] op_sel_hi:[0,1,1]
	v_pk_fma_f32 v[44:45], v[64:65], v[12:13], v[40:41] op_sel_hi:[0,1,1]
	v_pk_fma_f32 v[40:41], v[64:65], v[32:33], v[76:77] op_sel_hi:[0,1,1]
	v_mov_b32_e32 v10, v46
	v_mov_b32_e32 v11, v42
	v_mov_b32_e32 v12, v47
	v_mov_b32_e32 v13, v43
	v_pk_add_f32 v[10:11], v[10:11], v[12:13]
	v_mov_b32_e32 v12, v44
	v_mov_b32_e32 v13, v40
	v_mov_b32_e32 v30, v45
	v_mov_b32_e32 v31, v41
	v_pk_fma_f32 v[38:39], v[64:65], v[2:3], v[78:79] op_sel_hi:[0,1,1]
	v_pk_fma_f32 v[36:37], v[64:65], v[4:5], v[80:81] op_sel_hi:[0,1,1]
	v_pk_add_f32 v[12:13], v[12:13], v[30:31]
	v_pk_mov_b32 v[2:3], v[38:39], v[36:37] op_sel:[1,0]
	v_mov_b32_e32 v4, v38
	v_mov_b32_e32 v5, v37
	v_pk_add_f32 v[10:11], v[10:11], v[12:13]
	v_pk_add_f32 v[2:3], v[2:3], v[4:5]
	v_add_f32_e32 v10, 0, v10
	v_pk_add_f32 v[2:3], v[2:3], v[2:3] op_sel:[0,1] op_sel_hi:[1,0]
	v_pk_fma_f32 v[32:33], v[64:65], v[16:17], v[50:51] op_sel_hi:[0,1,1]
	v_pk_fma_f32 v[34:35], v[64:65], v[14:15], v[48:49] op_sel_hi:[0,1,1]
	v_pk_fma_f32 v[28:29], v[64:65], v[28:29], v[54:55] op_sel_hi:[0,1,1]
	v_pk_fma_f32 v[30:31], v[64:65], v[26:27], v[52:53] op_sel_hi:[0,1,1]
	v_add_f32_e32 v10, v10, v11
	v_add_f32_e32 v4, v34, v35
	v_add_f32_e32 v12, v32, v33
	v_mov_b32_e32 v11, v30
	v_mov_b32_e32 v3, v31
	v_mov_b32_e32 v5, v28
	v_mov_b32_e32 v13, v29
	v_pk_add_f32 v[2:3], v[10:11], v[2:3]
	v_pk_add_f32 v[4:5], v[4:5], v[12:13]
	v_pk_fma_f32 v[26:27], v[64:65], v[6:7], v[56:57] op_sel_hi:[0,1,1]
	v_pk_fma_f32 v[16:17], v[64:65], v[8:9], v[58:59] op_sel_hi:[0,1,1]
	v_pk_add_f32 v[2:3], v[2:3], v[4:5]
	v_pk_mov_b32 v[4:5], v[26:27], v[16:17] op_sel:[1,0]
	v_mov_b32_e32 v6, v26
	v_mov_b32_e32 v7, v17
	v_pk_add_f32 v[4:5], v[4:5], v[6:7]
	v_pk_add_f32 v[2:3], v[2:3], v[2:3] op_sel:[0,1] op_sel_hi:[1,0]
	v_pk_add_f32 v[4:5], v[4:5], v[4:5] op_sel:[0,1] op_sel_hi:[1,0]
	v_pk_fma_f32 v[10:11], v[64:65], v[20:21], v[62:63] op_sel_hi:[0,1,1]
	v_pk_fma_f32 v[12:13], v[64:65], v[18:19], v[60:61] op_sel_hi:[0,1,1]
	v_pk_fma_f32 v[6:7], v[64:65], v[24:25], v[72:73] op_sel_hi:[0,1,1]
	v_pk_fma_f32 v[8:9], v[64:65], v[22:23], v[70:71] op_sel_hi:[0,1,1]
	v_add_f32_e32 v14, v12, v13
	v_add_f32_e32 v18, v10, v11
	v_mov_b32_e32 v3, v8
	v_mov_b32_e32 v5, v9
	v_mov_b32_e32 v15, v6
	v_mov_b32_e32 v19, v7
	v_pk_add_f32 v[2:3], v[2:3], v[4:5]
	v_pk_add_f32 v[4:5], v[14:15], v[18:19]
	s_nop 0
	v_pk_add_f32 v[2:3], v[2:3], v[4:5]
	v_and_b32_e32 v4, 64, v240
	v_add_f32_e32 v2, v2, v3
	v_xor_b32_e32 v3, 16, v240
	v_add_u32_e32 v4, 64, v4
	v_cmp_lt_i32_e32 vcc, v3, v4
	s_nop 1
	v_cndmask_b32_e32 v3, v240, v3, vcc
	v_lshlrev_b32_e32 v20, 2, v3
	ds_bpermute_b32 v3, v20, v2
	s_waitcnt lgkmcnt(0)
	v_add_f32_e32 v2, v2, v3
	v_xor_b32_e32 v3, 32, v240
	v_cmp_lt_i32_e32 vcc, v3, v4
	s_nop 1
	v_cndmask_b32_e32 v3, v240, v3, vcc
	v_lshlrev_b32_e32 v21, 2, v3
	ds_bpermute_b32 v3, v21, v2
	s_waitcnt lgkmcnt(0)
; __device__ __forceinline__ void ret_unit(LAS unsigned char* lds, const bfu* PROJ, const bfu* RT, const float* gn_g, bfu* CAT, int u) {
;     ...
;     s += __shfl_xor(s, 16); s += __shfl_xor(s, 32); const float mu = s * (1.f / 128.f); float q = 0.f;
; #pragma unroll
;     for (int t = 0; t < 8; ++t) { acc[t] = acc[t] - mu; q += (acc[t][0] * acc[t][0] + acc[t][1] * acc[t][1]) + (acc[t][2] * acc[t][2] + acc[t][3] * acc[t][3]); }
;     q += __shfl_xor(q, 16); q += __shfl_xor(q, 32); const float rstd = 1.f / sqrtf(q * (1.f / 128.f) + EPS);
;     const bfu* gp = P0 + (size_t)c * INW + C_RG + 4 * fq; bfu* op = CAT + (row0 + c) * DM + h * 128 + 4 * fq; const float* gg = gn_g + h * 128 + 4 * fq;
; #pragma unroll
;     for (int t = 0; t < 8; ++t) { const v2u gw = *(const v2u*)(gp + 16 * t); const f32x4 g4 = *(const f32x4*)(gg + 16 * t);
	v_add_f32_e32 v22, v2, v3
	v_fmamk_f32 v47, v22, 0xbc000000, v47
	v_fmamk_f32 v43, v22, 0xbc000000, v43
	v_fmamk_f32 v45, v22, 0xbc000000, v45
	v_fmac_f32_e32 v46, 0xbc000000, v22
	v_fmamk_f32 v41, v22, 0xbc000000, v41
	v_fmac_f32_e32 v42, 0xbc000000, v22
	v_mov_b32_e32 v4, v47
	v_mov_b32_e32 v5, v43
	v_fmac_f32_e32 v44, 0xbc000000, v22
	v_fmac_f32_e32 v40, 0xbc000000, v22
	v_mov_b32_e32 v2, v46
	v_mov_b32_e32 v3, v42
	v_pk_mul_f32 v[4:5], v[4:5], v[4:5]
	v_mov_b32_e32 v14, v45
	v_mov_b32_e32 v15, v41
	v_pk_fma_f32 v[2:3], v[2:3], v[2:3], v[4:5]
	v_mov_b32_e32 v4, v44
	v_mov_b32_e32 v5, v40
	v_pk_mul_f32 v[14:15], v[14:15], v[14:15]
	v_fmamk_f32 v39, v22, 0xbc000000, v39
	v_pk_fma_f32 v[4:5], v[4:5], v[4:5], v[14:15]
	v_fmac_f32_e32 v38, 0xbc000000, v22
	v_pk_add_f32 v[2:3], v[2:3], v[4:5]
	v_fmamk_f32 v37, v22, 0xbc000000, v37
	v_fmac_f32_e32 v36, 0xbc000000, v22
	v_pk_add_f32 v[2:3], v[2:3], v[2:3] op_sel_hi:[0,1]
	v_pk_mul_f32 v[4:5], v[36:37], v[36:37]
	v_pk_mul_f32 v[14:15], v[38:39], v[38:39]
	v_fmac_f32_e32 v34, 0xbc000000, v22
	v_pk_mov_b32 v[18:19], v[14:15], v[4:5] op_sel:[1,0]
	v_mov_b32_e32 v15, v5
	v_fmac_f32_e32 v32, 0xbc000000, v22
	v_fmamk_f32 v35, v22, 0xbc000000, v35
	v_mul_f32_e32 v2, v34, v34
	v_pk_add_f32 v[4:5], v[18:19], v[14:15]
	v_fmamk_f32 v33, v22, 0xbc000000, v33
	v_pk_fma_f32 v[14:15], v[34:35], v[34:35], v[2:3] op_sel_hi:[1,1,0]
	v_mul_f32_e32 v2, v32, v32
	v_pk_add_f32 v[4:5], v[4:5], v[4:5] op_sel_hi:[0,1]
	v_pk_fma_f32 v[18:19], v[32:33], v[32:33], v[2:3] op_sel_hi:[1,1,0]
	v_fmamk_f32 v29, v22, 0xbc000000, v29
	v_fmac_f32_e32 v28, 0xbc000000, v22
	v_fmamk_f32 v31, v22, 0xbc000000, v31
	v_fmac_f32_e32 v30, 0xbc000000, v22
	v_mul_f32_e32 v14, v30, v30
	v_mul_f32_e32 v18, v31, v31
	v_mul_f32_e32 v4, v28, v28
	v_mul_f32_e32 v2, v29, v29
	v_pk_add_f32 v[14:15], v[14:15], v[18:19]
	v_pk_add_f32 v[2:3], v[4:5], v[2:3]
	v_fmamk_f32 v27, v22, 0xbc000000, v27
	v_pk_add_f32 v[2:3], v[14:15], v[2:3]
	v_fmac_f32_e32 v26, 0xbc000000, v22
	v_fmamk_f32 v17, v22, 0xbc000000, v17
	v_fmac_f32_e32 v16, 0xbc000000, v22
	v_pk_add_f32 v[2:3], v[2:3], v[2:3] op_sel_hi:[0,1]
	v_pk_mul_f32 v[4:5], v[16:17], v[16:17]
	v_pk_mul_f32 v[14:15], v[26:27], v[26:27]
	v_fmac_f32_e32 v12, 0xbc000000, v22
	v_pk_mov_b32 v[18:19], v[14:15], v[4:5] op_sel:[1,0]
	v_mov_b32_e32 v15, v5
	v_fmac_f32_e32 v10, 0xbc000000, v22
	v_fmamk_f32 v13, v22, 0xbc000000, v13
	v_mul_f32_e32 v2, v12, v12
	v_pk_add_f32 v[4:5], v[18:19], v[14:15]
	v_fmamk_f32 v11, v22, 0xbc000000, v11
	v_pk_fma_f32 v[14:15], v[12:13], v[12:13], v[2:3] op_sel_hi:[1,1,0]
	v_mul_f32_e32 v2, v10, v10
	v_pk_add_f32 v[4:5], v[4:5], v[4:5] op_sel_hi:[0,1]
	v_pk_fma_f32 v[18:19], v[10:11], v[10:11], v[2:3] op_sel_hi:[1,1,0]
	v_fmamk_f32 v7, v22, 0xbc000000, v7
	v_fmac_f32_e32 v6, 0xbc000000, v22
	v_fmamk_f32 v9, v22, 0xbc000000, v9
	v_fmac_f32_e32 v8, 0xbc000000, v22
	v_mul_f32_e32 v14, v8, v8
	v_mul_f32_e32 v18, v9, v9
	v_mul_f32_e32 v4, v6, v6
	v_mul_f32_e32 v2, v7, v7
	v_pk_add_f32 v[14:15], v[14:15], v[18:19]
	v_pk_add_f32 v[2:3], v[4:5], v[2:3]
	s_nop 0
	v_pk_add_f32 v[2:3], v[14:15], v[2:3]
	s_nop 0
	v_add_f32_e32 v2, v2, v3
	ds_bpermute_b32 v3, v20, v2
	s_waitcnt lgkmcnt(0)
	v_add_f32_e32 v2, v2, v3
	ds_bpermute_b32 v3, v21, v2
	s_waitcnt lgkmcnt(0)
	v_add_f32_e32 v2, v2, v3
	v_fmamk_f32 v2, v2, 0x3c000000, v236
	v_cmp_gt_f32_e32 vcc, s68, v2
	v_mul_f32_e32 v3, 0x4f800000, v2
	s_nop 0
	v_cndmask_b32_e32 v2, v2, v3, vcc
	v_sqrt_f32_e32 v3, v2
	s_nop 0
	v_add_u32_e32 v4, -1, v3
	v_fma_f32 v5, -v4, v3, v2
	v_cmp_ge_f32_e64 s[40:41], 0, v5
	v_add_u32_e32 v5, 1, v3
	s_nop 0
	v_cndmask_b32_e64 v4, v3, v4, s[40:41]
	v_fma_f32 v3, -v5, v3, v2
	v_cmp_lt_f32_e64 s[40:41], 0, v3
	s_nop 1
	v_cndmask_b32_e64 v3, v4, v5, s[40:41]
	v_mul_f32_e32 v4, 0x37800000, v3
	v_cndmask_b32_e32 v3, v3, v4, vcc
	v_cmp_class_f32_e32 vcc, v2, v234
	s_nop 1
	v_cndmask_b32_e32 v2, v3, v2, vcc
	v_div_scale_f32 v3, s[22:23], v2, v2, 1.0
	v_rcp_f32_e32 v4, v3
	s_nop 0
	v_fma_f32 v5, -v3, v4, 1.0
	v_fmac_f32_e32 v4, v5, v4
	v_div_scale_f32 v5, vcc, 1.0, v2, 1.0
	v_mul_f32_e32 v14, v5, v4
	v_fma_f32 v15, -v3, v14, v5
	v_fmac_f32_e32 v14, v15, v4
	v_fma_f32 v3, -v3, v14, v5
	v_div_fmas_f32 v3, v3, v4, v14
	v_lshl_add_u64 v[4:5], s[46:47], 0, v[66:67]
	v_div_fixup_f32 v14, v3, v2, 1.0
	v_mov_b64_e32 v[2:3], s[56:57]
	v_lshlrev_b64 v[4:5], 12, v[4:5]
	v_mad_i64_i32 v[2:3], s[22:23], v66, s61, v[2:3]
	v_lshl_add_u64 v[4:5], s[44:45], 0, v[4:5]
	v_lshl_add_u64 v[2:3], v[2:3], 0, v[0:1]
	s_mov_b64 s[22:23], 0x1200
	v_lshl_add_u64 v[4:5], v[4:5], 0, s[52:53]
	v_lshl_add_u64 v[20:21], v[2:3], 0, s[22:23]
	v_lshl_add_u64 v[22:23], v[4:5], 0, v[0:1]
	s_mov_b64 s[22:23], 0x29600000
	v_lshl_add_u64 v[18:19], v[22:23], 0, s[22:23]
	s_lshl_b64 s[22:23], s[50:51], 2
	v_add_co_u32_e32 v2, vcc, s62, v2
	s_add_u32 s40, s20, s22
	s_nop 0
	v_addc_co_u32_e32 v3, vcc, 0, v3, vcc
	s_addc_u32 s41, s35, s23
	global_load_dwordx2 v[120:121], v[2:3], off offset:512
	global_load_dwordx4 v[122:125], v69, s[40:41]
	global_load_dwordx2 v[126:127], v[20:21], off offset:32
	global_load_dwordx4 v[128:131], v69, s[40:41] offset:64
	global_load_dwordx2 v[132:133], v[20:21], off offset:64
	global_load_dwordx4 v[134:137], v69, s[40:41] offset:128
	global_load_dwordx2 v[138:139], v[20:21], off offset:96
	global_load_dwordx4 v[140:143], v69, s[40:41] offset:192
	global_load_dwordx2 v[144:145], v[20:21], off offset:128
	global_load_dwordx4 v[146:149], v69, s[40:41] offset:256
	global_load_dwordx2 v[150:151], v[20:21], off offset:160
	global_load_dwordx4 v[152:155], v69, s[40:41] offset:320
	global_load_dwordx2 v[156:157], v[20:21], off offset:192
	global_load_dwordx4 v[158:161], v69, s[40:41] offset:384
	global_load_dwordx2 v[162:163], v[20:21], off offset:224
	global_load_dwordx4 v[164:167], v69, s[40:41] offset:448
	s_nop 0
	s_mov_b32 s20, 0x29600000
	s_waitcnt vmcnt(0)
; __device__ __forceinline__ unsigned pk2(float lo, float hi) { return pg8::cvt_pk_bf16(lo, hi); }
; __device__ __forceinline__ float silu_f(float g) { return g * frcp(1.f + fexp2(-LOG2E * g)); }
; __device__ __forceinline__ void ret_unit(LAS unsigned char* lds, const bfu* PROJ, const bfu* RT, const float* gn_g, bfu* CAT, int u) {
;     ...
;     for (int t = 0; t < 8; ++t) { const v2u gw = *(const v2u*)(gp + 16 * t); const f32x4 g4 = *(const f32x4*)(gg + 16 * t);
;         const float o0 = silu_f(bflo(gw.x)) * acc[t][0] * rstd * g4.x, o1 = silu_f(bfhi(gw.x)) * acc[t][1] * rstd * g4.y, o2 = silu_f(bflo(gw.y)) * acc[t][2] * rstd * g4.z, o3 = silu_f(bfhi(gw.y)) * acc[t][3] * rstd * g4.w;
;         v2u w; w.x = pk2(o0, o1); w.y = pk2(o2, o3); *(v2u*)(op + 16 * t) = w; }
	v_lshlrev_b32_e32 v48, 16, v120
	v_mul_f32_e32 v0, 0xbfb8aa3b, v48
	v_exp_f32_e32 v0, v0
	v_and_b32_e32 v49, 0xffff0000, v120
	v_lshlrev_b32_e32 v24, 16, v121
	v_and_b32_e32 v25, 0xffff0000, v121
	v_add_f32_e32 v0, 1.0, v0
	v_rcp_f32_e32 v50, v0
	v_mul_f32_e32 v0, 0xbfb8aa3b, v49
	v_exp_f32_e32 v0, v0
	s_nop 0
	v_add_f32_e32 v0, 1.0, v0
	v_rcp_f32_e32 v51, v0
	v_mul_f32_e32 v0, 0xbfb8aa3b, v24
	v_exp_f32_e32 v0, v0
	v_pk_mul_f32 v[48:49], v[50:51], v[48:49]
	s_nop 0
	v_pk_mul_f32 v[46:47], v[46:47], v[48:49]
	v_add_f32_e32 v0, 1.0, v0
	v_pk_mul_f32 v[46:47], v[46:47], v[14:15] op_sel_hi:[1,0]
	v_pk_mul_f32 v[2:3], v[122:123], v[46:47]
	v_rcp_f32_e32 v46, v0
	v_mul_f32_e32 v0, 0xbfb8aa3b, v25
	v_exp_f32_e32 v0, v0
	v_cvt_pk_bf16_f32 v2, v2, v3
	v_add_f32_e32 v0, 1.0, v0
	v_rcp_f32_e32 v47, v0
	s_nop 0
	v_pk_mul_f32 v[24:25], v[46:47], v[24:25]
	s_nop 0
	v_pk_mul_f32 v[24:25], v[44:45], v[24:25]
	s_nop 0
	v_pk_mul_f32 v[24:25], v[24:25], v[14:15] op_sel_hi:[1,0]
	s_nop 0
	v_pk_mul_f32 v[4:5], v[124:125], v[24:25]
	s_nop 0
	v_cvt_pk_bf16_f32 v3, v4, v5
	v_add_co_u32_e32 v4, vcc, s20, v22
	s_nop 1
	v_addc_co_u32_e32 v5, vcc, 0, v23, vcc
	global_store_dwordx2 v[4:5], v[2:3], off
	s_nop 0
	v_lshlrev_b32_e32 v24, 16, v126
	v_mul_f32_e32 v0, 0xbfb8aa3b, v24
	v_exp_f32_e32 v0, v0
	v_and_b32_e32 v25, 0xffff0000, v126
	v_lshlrev_b32_e32 v22, 16, v127
	v_and_b32_e32 v23, 0xffff0000, v127
	v_add_f32_e32 v0, 1.0, v0
	v_rcp_f32_e32 v44, v0
	v_mul_f32_e32 v0, 0xbfb8aa3b, v25
	v_exp_f32_e32 v0, v0
	s_nop 0
	v_add_f32_e32 v0, 1.0, v0
	v_rcp_f32_e32 v45, v0
	v_mul_f32_e32 v0, 0xbfb8aa3b, v22
	v_exp_f32_e32 v0, v0
	v_pk_mul_f32 v[24:25], v[44:45], v[24:25]
	s_nop 0
	v_pk_mul_f32 v[24:25], v[42:43], v[24:25]
	v_add_f32_e32 v0, 1.0, v0
	v_pk_mul_f32 v[24:25], v[24:25], v[14:15] op_sel_hi:[1,0]
	v_pk_mul_f32 v[2:3], v[128:129], v[24:25]
	v_rcp_f32_e32 v24, v0
	v_mul_f32_e32 v0, 0xbfb8aa3b, v23
	v_exp_f32_e32 v0, v0
	v_cvt_pk_bf16_f32 v2, v2, v3
	v_add_f32_e32 v0, 1.0, v0
	v_rcp_f32_e32 v25, v0
	s_nop 0
	v_pk_mul_f32 v[22:23], v[24:25], v[22:23]
	s_nop 0
	v_pk_mul_f32 v[22:23], v[40:41], v[22:23]
	s_nop 0
	v_pk_mul_f32 v[22:23], v[22:23], v[14:15] op_sel_hi:[1,0]
	s_nop 0
	v_pk_mul_f32 v[4:5], v[130:131], v[22:23]
	s_nop 0
	v_cvt_pk_bf16_f32 v3, v4, v5
	global_store_dwordx2 v[18:19], v[2:3], off offset:32
	s_nop 0
	v_lshlrev_b32_e32 v24, 16, v132
	v_mul_f32_e32 v0, 0xbfb8aa3b, v24
	v_exp_f32_e32 v0, v0
	v_and_b32_e32 v25, 0xffff0000, v132
	v_lshlrev_b32_e32 v22, 16, v133
	v_and_b32_e32 v23, 0xffff0000, v133
	v_add_f32_e32 v0, 1.0, v0
	v_rcp_f32_e32 v40, v0
	v_mul_f32_e32 v0, 0xbfb8aa3b, v25
	v_exp_f32_e32 v0, v0
	s_nop 0
	v_add_f32_e32 v0, 1.0, v0
	v_rcp_f32_e32 v41, v0
	v_mul_f32_e32 v0, 0xbfb8aa3b, v22
	v_exp_f32_e32 v0, v0
	v_pk_mul_f32 v[24:25], v[40:41], v[24:25]
	s_nop 0
	v_pk_mul_f32 v[24:25], v[38:39], v[24:25]
	v_add_f32_e32 v0, 1.0, v0
	v_pk_mul_f32 v[24:25], v[24:25], v[14:15] op_sel_hi:[1,0]
	v_pk_mul_f32 v[2:3], v[134:135], v[24:25]
	v_rcp_f32_e32 v24, v0
	v_mul_f32_e32 v0, 0xbfb8aa3b, v23
	v_exp_f32_e32 v0, v0
	v_cvt_pk_bf16_f32 v2, v2, v3
	v_add_f32_e32 v0, 1.0, v0
	v_rcp_f32_e32 v25, v0
	s_nop 0
	v_pk_mul_f32 v[22:23], v[24:25], v[22:23]
	s_nop 0
	v_pk_mul_f32 v[22:23], v[36:37], v[22:23]
	s_nop 0
	v_pk_mul_f32 v[22:23], v[22:23], v[14:15] op_sel_hi:[1,0]
	s_nop 0
	v_pk_mul_f32 v[4:5], v[136:137], v[22:23]
	s_nop 0
	v_cvt_pk_bf16_f32 v3, v4, v5
	global_store_dwordx2 v[18:19], v[2:3], off offset:64
	s_nop 0
	v_lshlrev_b32_e32 v24, 16, v138
	v_mul_f32_e32 v0, 0xbfb8aa3b, v24
	v_exp_f32_e32 v0, v0
	v_and_b32_e32 v25, 0xffff0000, v138
	v_lshlrev_b32_e32 v22, 16, v139
	v_and_b32_e32 v23, 0xffff0000, v139
	v_add_f32_e32 v0, 1.0, v0
	v_rcp_f32_e32 v36, v0
	v_mul_f32_e32 v0, 0xbfb8aa3b, v25
	v_exp_f32_e32 v0, v0
	s_nop 0
	v_add_f32_e32 v0, 1.0, v0
	v_rcp_f32_e32 v37, v0
	v_mul_f32_e32 v0, 0xbfb8aa3b, v22
	v_exp_f32_e32 v0, v0
	v_pk_mul_f32 v[24:25], v[36:37], v[24:25]
	s_nop 0
	v_pk_mul_f32 v[24:25], v[34:35], v[24:25]
	v_add_f32_e32 v0, 1.0, v0
	v_pk_mul_f32 v[24:25], v[24:25], v[14:15] op_sel_hi:[1,0]
	v_pk_mul_f32 v[2:3], v[140:141], v[24:25]
	v_rcp_f32_e32 v24, v0
	v_mul_f32_e32 v0, 0xbfb8aa3b, v23
	v_exp_f32_e32 v0, v0
	v_cvt_pk_bf16_f32 v2, v2, v3
	v_add_f32_e32 v0, 1.0, v0
	v_rcp_f32_e32 v25, v0
	s_nop 0
	v_pk_mul_f32 v[22:23], v[24:25], v[22:23]
	s_nop 0
	v_pk_mul_f32 v[22:23], v[32:33], v[22:23]
	s_nop 0
	v_pk_mul_f32 v[22:23], v[22:23], v[14:15] op_sel_hi:[1,0]
	s_nop 0
	v_pk_mul_f32 v[4:5], v[142:143], v[22:23]
	s_nop 0
	v_cvt_pk_bf16_f32 v3, v4, v5
	global_store_dwordx2 v[18:19], v[2:3], off offset:96
; __device__ __forceinline__ unsigned pk2(float lo, float hi) { return pg8::cvt_pk_bf16(lo, hi); }
; __device__ __forceinline__ float silu_f(float g) { return g * frcp(1.f + fexp2(-LOG2E * g)); }
; __device__ __forceinline__ void ret_unit(LAS unsigned char* lds, const bfu* PROJ, const bfu* RT, const float* gn_g, bfu* CAT, int u) {
;     ...
;     for (int t = 0; t < 8; ++t) { const v2u gw = *(const v2u*)(gp + 16 * t); const f32x4 g4 = *(const f32x4*)(gg + 16 * t);
;         const float o0 = silu_f(bflo(gw.x)) * acc[t][0] * rstd * g4.x, o1 = silu_f(bfhi(gw.x)) * acc[t][1] * rstd * g4.y, o2 = silu_f(bflo(gw.y)) * acc[t][2] * rstd * g4.z, o3 = silu_f(bfhi(gw.y)) * acc[t][3] * rstd * g4.w;
;         v2u w; w.x = pk2(o0, o1); w.y = pk2(o2, o3); *(v2u*)(op + 16 * t) = w; }
;     __syncthreads();
	s_nop 0
	v_lshlrev_b32_e32 v24, 16, v144
	v_mul_f32_e32 v0, 0xbfb8aa3b, v24
	v_exp_f32_e32 v0, v0
	v_and_b32_e32 v25, 0xffff0000, v144
	v_lshlrev_b32_e32 v22, 16, v145
	v_and_b32_e32 v23, 0xffff0000, v145
	v_add_f32_e32 v0, 1.0, v0
	v_rcp_f32_e32 v32, v0
	v_mul_f32_e32 v0, 0xbfb8aa3b, v25
	v_exp_f32_e32 v0, v0
	s_nop 0
	v_add_f32_e32 v0, 1.0, v0
	v_rcp_f32_e32 v33, v0
	v_mul_f32_e32 v0, 0xbfb8aa3b, v22
	v_exp_f32_e32 v0, v0
	v_pk_mul_f32 v[24:25], v[32:33], v[24:25]
	s_nop 0
	v_pk_mul_f32 v[24:25], v[30:31], v[24:25]
	v_add_f32_e32 v0, 1.0, v0
	v_pk_mul_f32 v[24:25], v[24:25], v[14:15] op_sel_hi:[1,0]
	v_pk_mul_f32 v[2:3], v[146:147], v[24:25]
	v_rcp_f32_e32 v24, v0
	v_mul_f32_e32 v0, 0xbfb8aa3b, v23
	v_exp_f32_e32 v0, v0
	v_cvt_pk_bf16_f32 v2, v2, v3
	v_add_f32_e32 v0, 1.0, v0
	v_rcp_f32_e32 v25, v0
	s_nop 0
	v_pk_mul_f32 v[22:23], v[24:25], v[22:23]
	s_nop 0
	v_pk_mul_f32 v[22:23], v[28:29], v[22:23]
	s_nop 0
	v_pk_mul_f32 v[22:23], v[22:23], v[14:15] op_sel_hi:[1,0]
	s_nop 0
	v_pk_mul_f32 v[4:5], v[148:149], v[22:23]
	s_nop 0
	v_cvt_pk_bf16_f32 v3, v4, v5
	global_store_dwordx2 v[18:19], v[2:3], off offset:128
	s_nop 0
	v_lshlrev_b32_e32 v24, 16, v150
	v_mul_f32_e32 v0, 0xbfb8aa3b, v24
	v_exp_f32_e32 v0, v0
	v_and_b32_e32 v25, 0xffff0000, v150
	v_lshlrev_b32_e32 v22, 16, v151
	v_and_b32_e32 v23, 0xffff0000, v151
	v_add_f32_e32 v0, 1.0, v0
	v_rcp_f32_e32 v28, v0
	v_mul_f32_e32 v0, 0xbfb8aa3b, v25
	v_exp_f32_e32 v0, v0
	s_nop 0
	v_add_f32_e32 v0, 1.0, v0
	v_rcp_f32_e32 v29, v0
	v_mul_f32_e32 v0, 0xbfb8aa3b, v22
	v_exp_f32_e32 v0, v0
	v_pk_mul_f32 v[24:25], v[28:29], v[24:25]
	s_nop 0
	v_pk_mul_f32 v[24:25], v[26:27], v[24:25]
	v_add_f32_e32 v0, 1.0, v0
	v_pk_mul_f32 v[24:25], v[14:15], v[24:25] op_sel_hi:[0,1]
	v_pk_mul_f32 v[2:3], v[152:153], v[24:25]
	v_rcp_f32_e32 v24, v0
	v_mul_f32_e32 v0, 0xbfb8aa3b, v23
	v_exp_f32_e32 v0, v0
	v_cvt_pk_bf16_f32 v2, v2, v3
	v_add_f32_e32 v0, 1.0, v0
	v_rcp_f32_e32 v25, v0
	s_nop 0
	v_pk_mul_f32 v[22:23], v[24:25], v[22:23]
	s_nop 0
	v_pk_mul_f32 v[16:17], v[16:17], v[22:23]
	s_nop 0
	v_pk_mul_f32 v[16:17], v[14:15], v[16:17] op_sel_hi:[0,1]
	v_pk_mul_f32 v[4:5], v[154:155], v[16:17]
	s_nop 0
	v_cvt_pk_bf16_f32 v3, v4, v5
	global_store_dwordx2 v[18:19], v[2:3], off offset:160
	s_nop 0
	v_lshlrev_b32_e32 v22, 16, v156
	v_mul_f32_e32 v0, 0xbfb8aa3b, v22
	v_exp_f32_e32 v0, v0
	v_and_b32_e32 v23, 0xffff0000, v156
	v_add_f32_e32 v0, 1.0, v0
	v_rcp_f32_e32 v24, v0
	v_mul_f32_e32 v0, 0xbfb8aa3b, v23
	v_exp_f32_e32 v0, v0
	s_nop 0
	v_add_f32_e32 v0, 1.0, v0
	v_rcp_f32_e32 v25, v0
	s_nop 0
	v_pk_mul_f32 v[22:23], v[24:25], v[22:23]
	s_nop 0
	v_pk_mul_f32 v[12:13], v[12:13], v[22:23]
	s_nop 0
	v_pk_mul_f32 v[12:13], v[14:15], v[12:13] op_sel_hi:[0,1]
	v_pk_mul_f32 v[2:3], v[158:159], v[12:13]
	v_lshlrev_b32_e32 v12, 16, v157
	v_mul_f32_e32 v0, 0xbfb8aa3b, v12
	v_exp_f32_e32 v0, v0
	v_and_b32_e32 v13, 0xffff0000, v157
	v_cvt_pk_bf16_f32 v2, v2, v3
	v_add_f32_e32 v0, 1.0, v0
	v_rcp_f32_e32 v16, v0
	v_mul_f32_e32 v0, 0xbfb8aa3b, v13
	v_exp_f32_e32 v0, v0
	s_nop 0
	v_add_f32_e32 v0, 1.0, v0
	v_rcp_f32_e32 v17, v0
	s_nop 0
	v_pk_mul_f32 v[12:13], v[16:17], v[12:13]
	s_nop 0
	v_pk_mul_f32 v[10:11], v[10:11], v[12:13]
	s_nop 0
	v_pk_mul_f32 v[10:11], v[14:15], v[10:11] op_sel_hi:[0,1]
	v_pk_mul_f32 v[4:5], v[160:161], v[10:11]
	s_nop 0
	v_cvt_pk_bf16_f32 v3, v4, v5
	global_store_dwordx2 v[18:19], v[2:3], off offset:192
	s_nop 0
	v_lshlrev_b32_e32 v12, 16, v162
	v_mul_f32_e32 v0, 0xbfb8aa3b, v12
	v_exp_f32_e32 v0, v0
	v_and_b32_e32 v13, 0xffff0000, v162
	v_add_f32_e32 v0, 1.0, v0
	v_rcp_f32_e32 v16, v0
	v_mul_f32_e32 v0, 0xbfb8aa3b, v13
	v_exp_f32_e32 v0, v0
	s_nop 0
	v_add_f32_e32 v0, 1.0, v0
	v_rcp_f32_e32 v17, v0
	s_nop 0
	v_pk_mul_f32 v[12:13], v[16:17], v[12:13]
	s_nop 0
	v_pk_mul_f32 v[8:9], v[8:9], v[12:13]
	s_nop 0
	v_pk_mul_f32 v[8:9], v[14:15], v[8:9] op_sel_hi:[0,1]
	v_pk_mul_f32 v[2:3], v[164:165], v[8:9]
	v_lshlrev_b32_e32 v8, 16, v163
	v_mul_f32_e32 v0, 0xbfb8aa3b, v8
	v_exp_f32_e32 v0, v0
	v_and_b32_e32 v9, 0xffff0000, v163
	v_cvt_pk_bf16_f32 v2, v2, v3
	v_add_f32_e32 v0, 1.0, v0
	v_rcp_f32_e32 v10, v0
	v_mul_f32_e32 v0, 0xbfb8aa3b, v9
	v_exp_f32_e32 v0, v0
	s_nop 0
	v_add_f32_e32 v0, 1.0, v0
	v_rcp_f32_e32 v11, v0
	s_nop 0
	v_pk_mul_f32 v[8:9], v[10:11], v[8:9]
	s_nop 0
	v_pk_mul_f32 v[6:7], v[6:7], v[8:9]
	s_nop 0
	v_pk_mul_f32 v[6:7], v[14:15], v[6:7] op_sel_hi:[0,1]
	v_pk_mul_f32 v[4:5], v[166:167], v[6:7]
	s_nop 0
	v_cvt_pk_bf16_f32 v3, v4, v5
	global_store_dwordx2 v[18:19], v[2:3], off offset:224
	s_barrier

; __device__ __forceinline__ const float* karg(int k) { int kk = k; asm volatile("" : "+s"(kk)); return ((const float* const __attribute__((address_space(4)))*)__builtin_amdgcn_kernarg_segment_ptr())[kk]; }
; __device__ __forceinline__ void wait_ge(unsigned* word, unsigned want, unsigned* tmo) {
;     if (threadIdx.x == 0) {
;         unsigned sp = 0;
;         while (__hip_atomic_load(word, __ATOMIC_RELAXED, __HIP_MEMORY_SCOPE_AGENT) < want) {
;             __builtin_amdgcn_s_sleep(2);
;             if (++sp > (1u << 21)) { __hip_atomic_store(tmo, 1u, __ATOMIC_RELAXED, __HIP_MEMORY_SCOPE_AGENT); break; }
;             if ((sp & 1023u) == 0u && __hip_atomic_load(tmo, __ATOMIC_RELAXED, __HIP_MEMORY_SCOPE_AGENT)) break;
;         }
;         __builtin_amdgcn_fence(__ATOMIC_ACQUIRE, "agent");
;         asm volatile("s_waitcnt vmcnt(0)" ::: "memory");
;     }
;     __syncthreads();
; }
; __global__ void __launch_bounds__(NTHR, 2) fwd(Args args) {
;     ...
;                 if (u < 768) { wait_ge(cw + 128 + (u >> 6), 8u, cw + 192); ret_unit(lds, PROJ, RT, karg(3) + l * 768, CAT, u); }
.LBB0_423:
	s_ashr_i32 s34, s92, 6
	s_mov_b64 s[40:41], exec
	s_branch .LBB0_410
